# conv_tile main loop register-blocked over the 8 tokens: each staged row read+unpacked once and fed to all token accumulators (same per-token tap order)
# speedup vs baseline: 1.0022x; 1.0022x over previous
; DEV float bflo(unsigned u) { return __uint_as_float(u << 16); }
; DEV float bfhi(unsigned u) { return __uint_as_float(u & 0xffff0000u); }
; DEV void conv_tile(const Params& p, int tile, char* smem) {
;     ...
;   float w0[31], w1[31];
;   const float* cw = p.in[I_CONVW];
; #pragma unroll
;   for (int i = 0; i < 31; i++) { float2 t = *(const float2*)(cw + i * 512 + c); w0[i] = t.x; w1[i] = t.y; }
;   const float2 bb = *(const float2*)(p.in[I_CONVB] + c);
;   __syncthreads();
; #pragma unroll 1
;   for (int i = 0; i < 8; i++) {
;     float a0 = bb.x, a1 = bb.y;
; #pragma unroll
;     for (int wi = 0; wi < 31; wi++) {
;       unsigned u = *(const unsigned*)(stg + (i + wi) * 512 + c);
;       a0 += bflo(u) * w0[wi]; a1 += bfhi(u) * w1[wi];
;     }
;     *(float2*)(ybuf + i * 512 + c) = make_float2(a0, a1);
.LBB0_791:
	ds_read_b32 v153, v83
	ds_read_b32 v155, v83 offset:1024
	ds_read_b32 v157, v83 offset:2048
	ds_read_b32 v159, v83 offset:3072
	ds_read_b32 v161, v83 offset:4096
	ds_read_b32 v163, v83 offset:5120
	ds_read_b32 v165, v83 offset:6144
	ds_read_b32 v167, v83 offset:7168
	ds_read_b32 v169, v83 offset:8192
	ds_read_b32 v171, v83 offset:9216
	ds_read_b32 v173, v83 offset:10240
	ds_read_b32 v175, v83 offset:11264
	s_waitcnt vmcnt(0)
	s_waitcnt lgkmcnt(11)
	v_lshlrev_b32_e32 v152, 16, v153
	v_and_b32_e32 v153, 0xffff0000, v153
	v_pk_fma_f32 v[136:137], v[62:63], v[152:153], v[68:69]
	ds_read_b32 v153, v83 offset:12288
	s_waitcnt lgkmcnt(11)
	v_lshlrev_b32_e32 v154, 16, v155
	v_and_b32_e32 v155, 0xffff0000, v155
	v_pk_fma_f32 v[136:137], v[64:65], v[154:155], v[136:137]
	v_pk_fma_f32 v[138:139], v[62:63], v[154:155], v[68:69]
	ds_read_b32 v155, v83 offset:13312
	s_waitcnt lgkmcnt(11)
	v_lshlrev_b32_e32 v156, 16, v157
	v_and_b32_e32 v157, 0xffff0000, v157
	v_pk_fma_f32 v[136:137], v[52:53], v[156:157], v[136:137]
	v_pk_fma_f32 v[138:139], v[64:65], v[156:157], v[138:139]
	v_pk_fma_f32 v[140:141], v[62:63], v[156:157], v[68:69]
	ds_read_b32 v157, v83 offset:14336
	s_waitcnt lgkmcnt(11)
	v_lshlrev_b32_e32 v158, 16, v159
	v_and_b32_e32 v159, 0xffff0000, v159
	v_pk_fma_f32 v[136:137], v[54:55], v[158:159], v[136:137]
	v_pk_fma_f32 v[138:139], v[52:53], v[158:159], v[138:139]
	v_pk_fma_f32 v[140:141], v[64:65], v[158:159], v[140:141]
	v_pk_fma_f32 v[142:143], v[62:63], v[158:159], v[68:69]
	ds_read_b32 v159, v83 offset:15360
	s_waitcnt lgkmcnt(11)
	v_lshlrev_b32_e32 v160, 16, v161
	v_and_b32_e32 v161, 0xffff0000, v161
	v_pk_fma_f32 v[136:137], v[48:49], v[160:161], v[136:137]
	v_pk_fma_f32 v[138:139], v[54:55], v[160:161], v[138:139]
	v_pk_fma_f32 v[140:141], v[52:53], v[160:161], v[140:141]
	v_pk_fma_f32 v[142:143], v[64:65], v[160:161], v[142:143]
	v_pk_fma_f32 v[144:145], v[62:63], v[160:161], v[68:69]
	ds_read_b32 v161, v83 offset:16384
	s_waitcnt lgkmcnt(11)
	v_lshlrev_b32_e32 v162, 16, v163
	v_and_b32_e32 v163, 0xffff0000, v163
	v_pk_fma_f32 v[136:137], v[50:51], v[162:163], v[136:137]
	v_pk_fma_f32 v[138:139], v[48:49], v[162:163], v[138:139]
	v_pk_fma_f32 v[140:141], v[54:55], v[162:163], v[140:141]
	v_pk_fma_f32 v[142:143], v[52:53], v[162:163], v[142:143]
	v_pk_fma_f32 v[144:145], v[64:65], v[162:163], v[144:145]
	v_pk_fma_f32 v[146:147], v[62:63], v[162:163], v[68:69]
	ds_read_b32 v163, v83 offset:17408
	s_waitcnt lgkmcnt(11)
	v_lshlrev_b32_e32 v164, 16, v165
	v_and_b32_e32 v165, 0xffff0000, v165
	v_pk_fma_f32 v[136:137], v[56:57], v[164:165], v[136:137]
	v_pk_fma_f32 v[138:139], v[50:51], v[164:165], v[138:139]
	v_pk_fma_f32 v[140:141], v[48:49], v[164:165], v[140:141]
	v_pk_fma_f32 v[142:143], v[54:55], v[164:165], v[142:143]
	v_pk_fma_f32 v[144:145], v[52:53], v[164:165], v[144:145]
	v_pk_fma_f32 v[146:147], v[64:65], v[164:165], v[146:147]
	v_pk_fma_f32 v[148:149], v[62:63], v[164:165], v[68:69]
	ds_read_b32 v165, v83 offset:18432
	s_waitcnt lgkmcnt(11)
	v_lshlrev_b32_e32 v166, 16, v167
	v_and_b32_e32 v167, 0xffff0000, v167
	v_pk_fma_f32 v[136:137], v[58:59], v[166:167], v[136:137]
	v_pk_fma_f32 v[138:139], v[56:57], v[166:167], v[138:139]
	v_pk_fma_f32 v[140:141], v[50:51], v[166:167], v[140:141]
	v_pk_fma_f32 v[142:143], v[48:49], v[166:167], v[142:143]
	v_pk_fma_f32 v[144:145], v[54:55], v[166:167], v[144:145]
	v_pk_fma_f32 v[146:147], v[52:53], v[166:167], v[146:147]
	v_pk_fma_f32 v[148:149], v[64:65], v[166:167], v[148:149]
	v_pk_fma_f32 v[150:151], v[62:63], v[166:167], v[68:69]
	ds_read_b32 v167, v83 offset:19456
	s_waitcnt lgkmcnt(11)
	v_lshlrev_b32_e32 v168, 16, v169
	v_and_b32_e32 v169, 0xffff0000, v169
	v_pk_fma_f32 v[136:137], v[66:67], v[168:169], v[136:137]
	v_pk_fma_f32 v[138:139], v[58:59], v[168:169], v[138:139]
	v_pk_fma_f32 v[140:141], v[56:57], v[168:169], v[140:141]
	v_pk_fma_f32 v[142:143], v[50:51], v[168:169], v[142:143]
	v_pk_fma_f32 v[144:145], v[48:49], v[168:169], v[144:145]
	v_pk_fma_f32 v[146:147], v[54:55], v[168:169], v[146:147]
	v_pk_fma_f32 v[148:149], v[52:53], v[168:169], v[148:149]
	v_pk_fma_f32 v[150:151], v[64:65], v[168:169], v[150:151]
	ds_read_b32 v169, v83 offset:20480
	s_waitcnt lgkmcnt(11)
	v_lshlrev_b32_e32 v170, 16, v171
	v_and_b32_e32 v171, 0xffff0000, v171
	v_pk_fma_f32 v[136:137], v[60:61], v[170:171], v[136:137]
	v_pk_fma_f32 v[138:139], v[66:67], v[170:171], v[138:139]
	v_pk_fma_f32 v[140:141], v[58:59], v[170:171], v[140:141]
	v_pk_fma_f32 v[142:143], v[56:57], v[170:171], v[142:143]
	v_pk_fma_f32 v[144:145], v[50:51], v[170:171], v[144:145]
	v_pk_fma_f32 v[146:147], v[48:49], v[170:171], v[146:147]
	v_pk_fma_f32 v[148:149], v[54:55], v[170:171], v[148:149]
	v_pk_fma_f32 v[150:151], v[52:53], v[170:171], v[150:151]
	ds_read_b32 v171, v83 offset:21504
	s_waitcnt lgkmcnt(11)
	v_lshlrev_b32_e32 v172, 16, v173
	v_and_b32_e32 v173, 0xffff0000, v173
	v_pk_fma_f32 v[136:137], v[4:5], v[172:173], v[136:137]
	v_pk_fma_f32 v[138:139], v[60:61], v[172:173], v[138:139]
	v_pk_fma_f32 v[140:141], v[66:67], v[172:173], v[140:141]
	v_pk_fma_f32 v[142:143], v[58:59], v[172:173], v[142:143]
	v_pk_fma_f32 v[144:145], v[56:57], v[172:173], v[144:145]
	v_pk_fma_f32 v[146:147], v[50:51], v[172:173], v[146:147]
	v_pk_fma_f32 v[148:149], v[48:49], v[172:173], v[148:149]
	v_pk_fma_f32 v[150:151], v[54:55], v[172:173], v[150:151]
	ds_read_b32 v173, v83 offset:22528
	s_waitcnt lgkmcnt(11)
; DEV float bflo(unsigned u) { return __uint_as_float(u << 16); }
; DEV float bfhi(unsigned u) { return __uint_as_float(u & 0xffff0000u); }
; DEV void conv_tile(const Params& p, int tile, char* smem) {
;     ...
; #pragma unroll
;     for (int wi = 0; wi < 31; wi++) {
;       unsigned u = *(const unsigned*)(stg + (i + wi) * 512 + c);
;       a0 += bflo(u) * w0[wi]; a1 += bfhi(u) * w1[wi];
;     }
	v_lshlrev_b32_e32 v174, 16, v175
	v_and_b32_e32 v175, 0xffff0000, v175
	v_pk_fma_f32 v[136:137], v[6:7], v[174:175], v[136:137]
	v_pk_fma_f32 v[138:139], v[4:5], v[174:175], v[138:139]
	v_pk_fma_f32 v[140:141], v[60:61], v[174:175], v[140:141]
	v_pk_fma_f32 v[142:143], v[66:67], v[174:175], v[142:143]
	v_pk_fma_f32 v[144:145], v[58:59], v[174:175], v[144:145]
	v_pk_fma_f32 v[146:147], v[56:57], v[174:175], v[146:147]
	v_pk_fma_f32 v[148:149], v[50:51], v[174:175], v[148:149]
	v_pk_fma_f32 v[150:151], v[48:49], v[174:175], v[150:151]
	ds_read_b32 v175, v83 offset:23552
	s_waitcnt lgkmcnt(11)
	v_lshlrev_b32_e32 v152, 16, v153
	v_and_b32_e32 v153, 0xffff0000, v153
	v_pk_fma_f32 v[136:137], v[8:9], v[152:153], v[136:137]
	v_pk_fma_f32 v[138:139], v[6:7], v[152:153], v[138:139]
	v_pk_fma_f32 v[140:141], v[4:5], v[152:153], v[140:141]
	v_pk_fma_f32 v[142:143], v[60:61], v[152:153], v[142:143]
	v_pk_fma_f32 v[144:145], v[66:67], v[152:153], v[144:145]
	v_pk_fma_f32 v[146:147], v[58:59], v[152:153], v[146:147]
	v_pk_fma_f32 v[148:149], v[56:57], v[152:153], v[148:149]
	v_pk_fma_f32 v[150:151], v[50:51], v[152:153], v[150:151]
	ds_read_b32 v153, v83 offset:24576
	s_waitcnt lgkmcnt(11)
	v_lshlrev_b32_e32 v154, 16, v155
	v_and_b32_e32 v155, 0xffff0000, v155
	v_pk_fma_f32 v[136:137], v[10:11], v[154:155], v[136:137]
	v_pk_fma_f32 v[138:139], v[8:9], v[154:155], v[138:139]
	v_pk_fma_f32 v[140:141], v[6:7], v[154:155], v[140:141]
	v_pk_fma_f32 v[142:143], v[4:5], v[154:155], v[142:143]
	v_pk_fma_f32 v[144:145], v[60:61], v[154:155], v[144:145]
	v_pk_fma_f32 v[146:147], v[66:67], v[154:155], v[146:147]
	v_pk_fma_f32 v[148:149], v[58:59], v[154:155], v[148:149]
	v_pk_fma_f32 v[150:151], v[56:57], v[154:155], v[150:151]
	ds_read_b32 v155, v83 offset:25600
	s_waitcnt lgkmcnt(11)
	v_lshlrev_b32_e32 v156, 16, v157
	v_and_b32_e32 v157, 0xffff0000, v157
	v_pk_fma_f32 v[136:137], v[12:13], v[156:157], v[136:137]
	v_pk_fma_f32 v[138:139], v[10:11], v[156:157], v[138:139]
	v_pk_fma_f32 v[140:141], v[8:9], v[156:157], v[140:141]
	v_pk_fma_f32 v[142:143], v[6:7], v[156:157], v[142:143]
	v_pk_fma_f32 v[144:145], v[4:5], v[156:157], v[144:145]
	v_pk_fma_f32 v[146:147], v[60:61], v[156:157], v[146:147]
	v_pk_fma_f32 v[148:149], v[66:67], v[156:157], v[148:149]
	v_pk_fma_f32 v[150:151], v[58:59], v[156:157], v[150:151]
	ds_read_b32 v157, v83 offset:26624
	s_waitcnt lgkmcnt(11)
	v_lshlrev_b32_e32 v158, 16, v159
	v_and_b32_e32 v159, 0xffff0000, v159
	v_pk_fma_f32 v[136:137], v[14:15], v[158:159], v[136:137]
	v_pk_fma_f32 v[138:139], v[12:13], v[158:159], v[138:139]
	v_pk_fma_f32 v[140:141], v[10:11], v[158:159], v[140:141]
	v_pk_fma_f32 v[142:143], v[8:9], v[158:159], v[142:143]
	v_pk_fma_f32 v[144:145], v[6:7], v[158:159], v[144:145]
	v_pk_fma_f32 v[146:147], v[4:5], v[158:159], v[146:147]
	v_pk_fma_f32 v[148:149], v[60:61], v[158:159], v[148:149]
	v_pk_fma_f32 v[150:151], v[66:67], v[158:159], v[150:151]
	ds_read_b32 v159, v83 offset:27648
	s_waitcnt lgkmcnt(11)
	v_lshlrev_b32_e32 v160, 16, v161
	v_and_b32_e32 v161, 0xffff0000, v161
	v_pk_fma_f32 v[136:137], v[16:17], v[160:161], v[136:137]
	v_pk_fma_f32 v[138:139], v[14:15], v[160:161], v[138:139]
	v_pk_fma_f32 v[140:141], v[12:13], v[160:161], v[140:141]
	v_pk_fma_f32 v[142:143], v[10:11], v[160:161], v[142:143]
	v_pk_fma_f32 v[144:145], v[8:9], v[160:161], v[144:145]
	v_pk_fma_f32 v[146:147], v[6:7], v[160:161], v[146:147]
	v_pk_fma_f32 v[148:149], v[4:5], v[160:161], v[148:149]
	v_pk_fma_f32 v[150:151], v[60:61], v[160:161], v[150:151]
	ds_read_b32 v161, v83 offset:28672
	s_waitcnt lgkmcnt(11)
	v_lshlrev_b32_e32 v162, 16, v163
	v_and_b32_e32 v163, 0xffff0000, v163
	v_pk_fma_f32 v[136:137], v[20:21], v[162:163], v[136:137]
	v_pk_fma_f32 v[138:139], v[16:17], v[162:163], v[138:139]
	v_pk_fma_f32 v[140:141], v[14:15], v[162:163], v[140:141]
	v_pk_fma_f32 v[142:143], v[12:13], v[162:163], v[142:143]
	v_pk_fma_f32 v[144:145], v[10:11], v[162:163], v[144:145]
	v_pk_fma_f32 v[146:147], v[8:9], v[162:163], v[146:147]
	v_pk_fma_f32 v[148:149], v[6:7], v[162:163], v[148:149]
	v_pk_fma_f32 v[150:151], v[4:5], v[162:163], v[150:151]
	ds_read_b32 v163, v83 offset:29696
	s_waitcnt lgkmcnt(11)
	v_lshlrev_b32_e32 v164, 16, v165
	v_and_b32_e32 v165, 0xffff0000, v165
	v_pk_fma_f32 v[136:137], v[22:23], v[164:165], v[136:137]
	v_pk_fma_f32 v[138:139], v[20:21], v[164:165], v[138:139]
	v_pk_fma_f32 v[140:141], v[16:17], v[164:165], v[140:141]
	v_pk_fma_f32 v[142:143], v[14:15], v[164:165], v[142:143]
	v_pk_fma_f32 v[144:145], v[12:13], v[164:165], v[144:145]
	v_pk_fma_f32 v[146:147], v[10:11], v[164:165], v[146:147]
	v_pk_fma_f32 v[148:149], v[8:9], v[164:165], v[148:149]
	v_pk_fma_f32 v[150:151], v[6:7], v[164:165], v[150:151]
	ds_read_b32 v165, v83 offset:30720
	s_waitcnt lgkmcnt(11)
	v_lshlrev_b32_e32 v166, 16, v167
	v_and_b32_e32 v167, 0xffff0000, v167
	v_pk_fma_f32 v[136:137], v[24:25], v[166:167], v[136:137]
	v_pk_fma_f32 v[138:139], v[22:23], v[166:167], v[138:139]
	v_pk_fma_f32 v[140:141], v[20:21], v[166:167], v[140:141]
	v_pk_fma_f32 v[142:143], v[16:17], v[166:167], v[142:143]
	v_pk_fma_f32 v[144:145], v[14:15], v[166:167], v[144:145]
	v_pk_fma_f32 v[146:147], v[12:13], v[166:167], v[146:147]
	v_pk_fma_f32 v[148:149], v[10:11], v[166:167], v[148:149]
	v_pk_fma_f32 v[150:151], v[8:9], v[166:167], v[150:151]
	ds_read_b32 v167, v83 offset:31744
	s_waitcnt lgkmcnt(11)
; DEV float bflo(unsigned u) { return __uint_as_float(u << 16); }
; DEV float bfhi(unsigned u) { return __uint_as_float(u & 0xffff0000u); }
; DEV void conv_tile(const Params& p, int tile, char* smem) {
;     ...
; #pragma unroll 1
;   for (int i = 0; i < 8; i++) {
;     float a0 = bb.x, a1 = bb.y;
; #pragma unroll
;     for (int wi = 0; wi < 31; wi++) {
;       unsigned u = *(const unsigned*)(stg + (i + wi) * 512 + c);
;       a0 += bflo(u) * w0[wi]; a1 += bfhi(u) * w1[wi];
;     }
	v_lshlrev_b32_e32 v168, 16, v169
	v_and_b32_e32 v169, 0xffff0000, v169
	v_pk_fma_f32 v[136:137], v[26:27], v[168:169], v[136:137]
	v_pk_fma_f32 v[138:139], v[24:25], v[168:169], v[138:139]
	v_pk_fma_f32 v[140:141], v[22:23], v[168:169], v[140:141]
	v_pk_fma_f32 v[142:143], v[20:21], v[168:169], v[142:143]
	v_pk_fma_f32 v[144:145], v[16:17], v[168:169], v[144:145]
	v_pk_fma_f32 v[146:147], v[14:15], v[168:169], v[146:147]
	v_pk_fma_f32 v[148:149], v[12:13], v[168:169], v[148:149]
	v_pk_fma_f32 v[150:151], v[10:11], v[168:169], v[150:151]
	ds_read_b32 v169, v83 offset:32768
	s_waitcnt lgkmcnt(11)
	v_lshlrev_b32_e32 v170, 16, v171
	v_and_b32_e32 v171, 0xffff0000, v171
	v_pk_fma_f32 v[136:137], v[28:29], v[170:171], v[136:137]
	v_pk_fma_f32 v[138:139], v[26:27], v[170:171], v[138:139]
	v_pk_fma_f32 v[140:141], v[24:25], v[170:171], v[140:141]
	v_pk_fma_f32 v[142:143], v[22:23], v[170:171], v[142:143]
	v_pk_fma_f32 v[144:145], v[20:21], v[170:171], v[144:145]
	v_pk_fma_f32 v[146:147], v[16:17], v[170:171], v[146:147]
	v_pk_fma_f32 v[148:149], v[14:15], v[170:171], v[148:149]
	v_pk_fma_f32 v[150:151], v[12:13], v[170:171], v[150:151]
	ds_read_b32 v171, v83 offset:33792
	s_waitcnt lgkmcnt(11)
	v_lshlrev_b32_e32 v172, 16, v173
	v_and_b32_e32 v173, 0xffff0000, v173
	v_pk_fma_f32 v[136:137], v[30:31], v[172:173], v[136:137]
	v_pk_fma_f32 v[138:139], v[28:29], v[172:173], v[138:139]
	v_pk_fma_f32 v[140:141], v[26:27], v[172:173], v[140:141]
	v_pk_fma_f32 v[142:143], v[24:25], v[172:173], v[142:143]
	v_pk_fma_f32 v[144:145], v[22:23], v[172:173], v[144:145]
	v_pk_fma_f32 v[146:147], v[20:21], v[172:173], v[146:147]
	v_pk_fma_f32 v[148:149], v[16:17], v[172:173], v[148:149]
	v_pk_fma_f32 v[150:151], v[14:15], v[172:173], v[150:151]
	ds_read_b32 v173, v83 offset:34816
	s_waitcnt lgkmcnt(11)
	v_lshlrev_b32_e32 v174, 16, v175
	v_and_b32_e32 v175, 0xffff0000, v175
	v_pk_fma_f32 v[136:137], v[32:33], v[174:175], v[136:137]
	v_pk_fma_f32 v[138:139], v[30:31], v[174:175], v[138:139]
	v_pk_fma_f32 v[140:141], v[28:29], v[174:175], v[140:141]
	v_pk_fma_f32 v[142:143], v[26:27], v[174:175], v[142:143]
	v_pk_fma_f32 v[144:145], v[24:25], v[174:175], v[144:145]
	v_pk_fma_f32 v[146:147], v[22:23], v[174:175], v[146:147]
	v_pk_fma_f32 v[148:149], v[20:21], v[174:175], v[148:149]
	v_pk_fma_f32 v[150:151], v[16:17], v[174:175], v[150:151]
	ds_read_b32 v175, v83 offset:35840
	s_waitcnt lgkmcnt(11)
	v_lshlrev_b32_e32 v152, 16, v153
	v_and_b32_e32 v153, 0xffff0000, v153
	v_pk_fma_f32 v[136:137], v[34:35], v[152:153], v[136:137]
	v_pk_fma_f32 v[138:139], v[32:33], v[152:153], v[138:139]
	v_pk_fma_f32 v[140:141], v[30:31], v[152:153], v[140:141]
	v_pk_fma_f32 v[142:143], v[28:29], v[152:153], v[142:143]
	v_pk_fma_f32 v[144:145], v[26:27], v[152:153], v[144:145]
	v_pk_fma_f32 v[146:147], v[24:25], v[152:153], v[146:147]
	v_pk_fma_f32 v[148:149], v[22:23], v[152:153], v[148:149]
	v_pk_fma_f32 v[150:151], v[20:21], v[152:153], v[150:151]
	ds_read_b32 v153, v83 offset:36864
	s_waitcnt lgkmcnt(11)
	v_lshlrev_b32_e32 v154, 16, v155
	v_and_b32_e32 v155, 0xffff0000, v155
	v_pk_fma_f32 v[136:137], v[36:37], v[154:155], v[136:137]
	v_pk_fma_f32 v[138:139], v[34:35], v[154:155], v[138:139]
	v_pk_fma_f32 v[140:141], v[32:33], v[154:155], v[140:141]
	v_pk_fma_f32 v[142:143], v[30:31], v[154:155], v[142:143]
	v_pk_fma_f32 v[144:145], v[28:29], v[154:155], v[144:145]
	v_pk_fma_f32 v[146:147], v[26:27], v[154:155], v[146:147]
	v_pk_fma_f32 v[148:149], v[24:25], v[154:155], v[148:149]
	v_pk_fma_f32 v[150:151], v[22:23], v[154:155], v[150:151]
	ds_read_b32 v155, v83 offset:37888
	s_waitcnt lgkmcnt(11)
	v_lshlrev_b32_e32 v156, 16, v157
	v_and_b32_e32 v157, 0xffff0000, v157
	v_pk_fma_f32 v[136:137], v[38:39], v[156:157], v[136:137]
	v_pk_fma_f32 v[138:139], v[36:37], v[156:157], v[138:139]
	v_pk_fma_f32 v[140:141], v[34:35], v[156:157], v[140:141]
	v_pk_fma_f32 v[142:143], v[32:33], v[156:157], v[142:143]
	v_pk_fma_f32 v[144:145], v[30:31], v[156:157], v[144:145]
	v_pk_fma_f32 v[146:147], v[28:29], v[156:157], v[146:147]
	v_pk_fma_f32 v[148:149], v[26:27], v[156:157], v[148:149]
	v_pk_fma_f32 v[150:151], v[24:25], v[156:157], v[150:151]
	s_waitcnt lgkmcnt(10)
	v_lshlrev_b32_e32 v158, 16, v159
	v_and_b32_e32 v159, 0xffff0000, v159
	v_pk_fma_f32 v[136:137], v[40:41], v[158:159], v[136:137]
	v_pk_fma_f32 v[138:139], v[38:39], v[158:159], v[138:139]
	v_pk_fma_f32 v[140:141], v[36:37], v[158:159], v[140:141]
	v_pk_fma_f32 v[142:143], v[34:35], v[158:159], v[142:143]
	v_pk_fma_f32 v[144:145], v[32:33], v[158:159], v[144:145]
	v_pk_fma_f32 v[146:147], v[30:31], v[158:159], v[146:147]
	v_pk_fma_f32 v[148:149], v[28:29], v[158:159], v[148:149]
	v_pk_fma_f32 v[150:151], v[26:27], v[158:159], v[150:151]
	s_waitcnt lgkmcnt(9)
	v_lshlrev_b32_e32 v160, 16, v161
	v_and_b32_e32 v161, 0xffff0000, v161
	v_pk_fma_f32 v[136:137], v[42:43], v[160:161], v[136:137]
	v_pk_fma_f32 v[138:139], v[40:41], v[160:161], v[138:139]
	v_pk_fma_f32 v[140:141], v[38:39], v[160:161], v[140:141]
	v_pk_fma_f32 v[142:143], v[36:37], v[160:161], v[142:143]
	v_pk_fma_f32 v[144:145], v[34:35], v[160:161], v[144:145]
	v_pk_fma_f32 v[146:147], v[32:33], v[160:161], v[146:147]
	v_pk_fma_f32 v[148:149], v[30:31], v[160:161], v[148:149]
	v_pk_fma_f32 v[150:151], v[28:29], v[160:161], v[150:151]
	s_waitcnt lgkmcnt(8)
	v_lshlrev_b32_e32 v162, 16, v163
	v_and_b32_e32 v163, 0xffff0000, v163
	v_pk_fma_f32 v[136:137], v[44:45], v[162:163], v[136:137]
	v_pk_fma_f32 v[138:139], v[42:43], v[162:163], v[138:139]
	v_pk_fma_f32 v[140:141], v[40:41], v[162:163], v[140:141]
	v_pk_fma_f32 v[142:143], v[38:39], v[162:163], v[142:143]
	v_pk_fma_f32 v[144:145], v[36:37], v[162:163], v[144:145]
	v_pk_fma_f32 v[146:147], v[34:35], v[162:163], v[146:147]
	v_pk_fma_f32 v[148:149], v[32:33], v[162:163], v[148:149]
	v_pk_fma_f32 v[150:151], v[30:31], v[162:163], v[150:151]
	s_waitcnt lgkmcnt(7)
; DEV float bflo(unsigned u) { return __uint_as_float(u << 16); }
; DEV float bfhi(unsigned u) { return __uint_as_float(u & 0xffff0000u); }
; DEV void conv_tile(const Params& p, int tile, char* smem) {
;     ...
;   for (int i = 0; i < 8; i++) {
;     float a0 = bb.x, a1 = bb.y;
; #pragma unroll
;     for (int wi = 0; wi < 31; wi++) {
;       unsigned u = *(const unsigned*)(stg + (i + wi) * 512 + c);
;       a0 += bflo(u) * w0[wi]; a1 += bfhi(u) * w1[wi];
;     }
;     *(float2*)(ybuf + i * 512 + c) = make_float2(a0, a1);
;     float s1 = wave_sum(a0 + a1);
;     float s2 = wave_sum(a0 * a0 + a1 * a1);
;     if (lane == 0) { red[(i * 4 + w) * 2] = s1; red[(i * 4 + w) * 2 + 1] = s2; }
	v_lshlrev_b32_e32 v164, 16, v165
	v_and_b32_e32 v165, 0xffff0000, v165
	v_pk_fma_f32 v[136:137], v[46:47], v[164:165], v[136:137]
	v_pk_fma_f32 v[138:139], v[44:45], v[164:165], v[138:139]
	v_pk_fma_f32 v[140:141], v[42:43], v[164:165], v[140:141]
	v_pk_fma_f32 v[142:143], v[40:41], v[164:165], v[142:143]
	v_pk_fma_f32 v[144:145], v[38:39], v[164:165], v[144:145]
	v_pk_fma_f32 v[146:147], v[36:37], v[164:165], v[146:147]
	v_pk_fma_f32 v[148:149], v[34:35], v[164:165], v[148:149]
	v_pk_fma_f32 v[150:151], v[32:33], v[164:165], v[150:151]
	s_waitcnt lgkmcnt(6)
	v_lshlrev_b32_e32 v166, 16, v167
	v_and_b32_e32 v167, 0xffff0000, v167
	v_pk_fma_f32 v[138:139], v[46:47], v[166:167], v[138:139]
	v_pk_fma_f32 v[140:141], v[44:45], v[166:167], v[140:141]
	v_pk_fma_f32 v[142:143], v[42:43], v[166:167], v[142:143]
	v_pk_fma_f32 v[144:145], v[40:41], v[166:167], v[144:145]
	v_pk_fma_f32 v[146:147], v[38:39], v[166:167], v[146:147]
	v_pk_fma_f32 v[148:149], v[36:37], v[166:167], v[148:149]
	v_pk_fma_f32 v[150:151], v[34:35], v[166:167], v[150:151]
	s_waitcnt lgkmcnt(5)
	v_lshlrev_b32_e32 v168, 16, v169
	v_and_b32_e32 v169, 0xffff0000, v169
	v_pk_fma_f32 v[140:141], v[46:47], v[168:169], v[140:141]
	v_pk_fma_f32 v[142:143], v[44:45], v[168:169], v[142:143]
	v_pk_fma_f32 v[144:145], v[42:43], v[168:169], v[144:145]
	v_pk_fma_f32 v[146:147], v[40:41], v[168:169], v[146:147]
	v_pk_fma_f32 v[148:149], v[38:39], v[168:169], v[148:149]
	v_pk_fma_f32 v[150:151], v[36:37], v[168:169], v[150:151]
	s_waitcnt lgkmcnt(4)
	v_lshlrev_b32_e32 v170, 16, v171
	v_and_b32_e32 v171, 0xffff0000, v171
	v_pk_fma_f32 v[142:143], v[46:47], v[170:171], v[142:143]
	v_pk_fma_f32 v[144:145], v[44:45], v[170:171], v[144:145]
	v_pk_fma_f32 v[146:147], v[42:43], v[170:171], v[146:147]
	v_pk_fma_f32 v[148:149], v[40:41], v[170:171], v[148:149]
	v_pk_fma_f32 v[150:151], v[38:39], v[170:171], v[150:151]
	s_waitcnt lgkmcnt(3)
	v_lshlrev_b32_e32 v172, 16, v173
	v_and_b32_e32 v173, 0xffff0000, v173
	v_pk_fma_f32 v[144:145], v[46:47], v[172:173], v[144:145]
	v_pk_fma_f32 v[146:147], v[44:45], v[172:173], v[146:147]
	v_pk_fma_f32 v[148:149], v[42:43], v[172:173], v[148:149]
	v_pk_fma_f32 v[150:151], v[40:41], v[172:173], v[150:151]
	s_waitcnt lgkmcnt(2)
	v_lshlrev_b32_e32 v174, 16, v175
	v_and_b32_e32 v175, 0xffff0000, v175
	v_pk_fma_f32 v[146:147], v[46:47], v[174:175], v[146:147]
	v_pk_fma_f32 v[148:149], v[44:45], v[174:175], v[148:149]
	v_pk_fma_f32 v[150:151], v[42:43], v[174:175], v[150:151]
	s_waitcnt lgkmcnt(1)
	v_lshlrev_b32_e32 v152, 16, v153
	v_and_b32_e32 v153, 0xffff0000, v153
	v_pk_fma_f32 v[148:149], v[46:47], v[152:153], v[148:149]
	v_pk_fma_f32 v[150:151], v[44:45], v[152:153], v[150:151]
	s_waitcnt lgkmcnt(0)
	v_lshlrev_b32_e32 v154, 16, v155
	v_and_b32_e32 v155, 0xffff0000, v155
	v_pk_fma_f32 v[150:151], v[46:47], v[154:155], v[150:151]
	ds_write_b64 v82, v[136:137]
	v_pk_mul_f32 v[72:73], v[136:137], v[136:137]
	v_mov_b32_e32 v84, v137
	v_mov_b32_e32 v85, v73
	v_mov_b32_e32 v137, v72
	v_pk_add_f32 v[104:105], v[84:85], v[136:137]
	ds_write_b64 v82, v[138:139] offset:2048
	v_pk_mul_f32 v[72:73], v[138:139], v[138:139]
	v_mov_b32_e32 v84, v139
	v_mov_b32_e32 v85, v73
	v_mov_b32_e32 v139, v72
	v_pk_add_f32 v[106:107], v[84:85], v[138:139]
	ds_write_b64 v82, v[140:141] offset:4096
	v_pk_mul_f32 v[72:73], v[140:141], v[140:141]
	v_mov_b32_e32 v84, v141
	v_mov_b32_e32 v85, v73
	v_mov_b32_e32 v141, v72
	v_pk_add_f32 v[108:109], v[84:85], v[140:141]
	ds_write_b64 v82, v[142:143] offset:6144
	v_pk_mul_f32 v[72:73], v[142:143], v[142:143]
	v_mov_b32_e32 v84, v143
	v_mov_b32_e32 v85, v73
	v_mov_b32_e32 v143, v72
	v_pk_add_f32 v[110:111], v[84:85], v[142:143]
	ds_write_b64 v82, v[144:145] offset:8192
	v_pk_mul_f32 v[72:73], v[144:145], v[144:145]
	v_mov_b32_e32 v84, v145
	v_mov_b32_e32 v85, v73
	v_mov_b32_e32 v145, v72
	v_pk_add_f32 v[112:113], v[84:85], v[144:145]
	ds_write_b64 v82, v[146:147] offset:10240
	v_pk_mul_f32 v[72:73], v[146:147], v[146:147]
	v_mov_b32_e32 v84, v147
	v_mov_b32_e32 v85, v73
	v_mov_b32_e32 v147, v72
	v_pk_add_f32 v[114:115], v[84:85], v[146:147]
	ds_write_b64 v82, v[148:149] offset:12288
	v_pk_mul_f32 v[72:73], v[148:149], v[148:149]
	v_mov_b32_e32 v84, v149
	v_mov_b32_e32 v85, v73
	v_mov_b32_e32 v149, v72
	v_pk_add_f32 v[116:117], v[84:85], v[148:149]
	ds_write_b64 v82, v[150:151] offset:14336
	v_pk_mul_f32 v[72:73], v[150:151], v[150:151]
	v_mov_b32_e32 v84, v151
	v_mov_b32_e32 v85, v73
	v_mov_b32_e32 v151, v72
	v_pk_add_f32 v[118:119], v[84:85], v[150:151]
	ds_bpermute_b32 v120, v75, v104
	ds_bpermute_b32 v121, v75, v105
	ds_bpermute_b32 v122, v75, v106
	ds_bpermute_b32 v123, v75, v107
	ds_bpermute_b32 v124, v75, v108
	ds_bpermute_b32 v125, v75, v109
	ds_bpermute_b32 v126, v75, v110
	ds_bpermute_b32 v127, v75, v111
	ds_bpermute_b32 v128, v75, v112
	ds_bpermute_b32 v129, v75, v113
	ds_bpermute_b32 v130, v75, v114
	ds_bpermute_b32 v131, v75, v115
	ds_bpermute_b32 v132, v75, v116
	ds_bpermute_b32 v133, v75, v117
	ds_bpermute_b32 v134, v75, v118
	ds_bpermute_b32 v135, v75, v119
	s_waitcnt lgkmcnt(14)
	v_pk_add_f32 v[104:105], v[104:105], v[120:121]
	s_waitcnt lgkmcnt(12)
	v_pk_add_f32 v[106:107], v[106:107], v[122:123]
	s_waitcnt lgkmcnt(10)
	v_pk_add_f32 v[108:109], v[108:109], v[124:125]
	s_waitcnt lgkmcnt(8)
	v_pk_add_f32 v[110:111], v[110:111], v[126:127]
	s_waitcnt lgkmcnt(6)
	v_pk_add_f32 v[112:113], v[112:113], v[128:129]
	s_waitcnt lgkmcnt(4)
	v_pk_add_f32 v[114:115], v[114:115], v[130:131]
	s_waitcnt lgkmcnt(2)
	v_pk_add_f32 v[116:117], v[116:117], v[132:133]
	s_waitcnt lgkmcnt(0)
; DEV float wave_sum(float v) {
; #pragma unroll
;   for (int o = 32; o > 0; o >>= 1) v += __shfl_xor(v, o);
;   return v;
; }
; DEV void conv_tile(const Params& p, int tile, char* smem) {
;     ...
;     float s1 = wave_sum(a0 + a1);
;     float s2 = wave_sum(a0 * a0 + a1 * a1);
;     if (lane == 0) { red[(i * 4 + w) * 2] = s1; red[(i * 4 + w) * 2 + 1] = s2; }
	v_pk_add_f32 v[118:119], v[118:119], v[134:135]
	ds_bpermute_b32 v120, v76, v104
	ds_bpermute_b32 v121, v76, v105
	ds_bpermute_b32 v122, v76, v106
	ds_bpermute_b32 v123, v76, v107
	ds_bpermute_b32 v124, v76, v108
	ds_bpermute_b32 v125, v76, v109
	ds_bpermute_b32 v126, v76, v110
	ds_bpermute_b32 v127, v76, v111
	ds_bpermute_b32 v128, v76, v112
	ds_bpermute_b32 v129, v76, v113
	ds_bpermute_b32 v130, v76, v114
	ds_bpermute_b32 v131, v76, v115
	ds_bpermute_b32 v132, v76, v116
	ds_bpermute_b32 v133, v76, v117
	ds_bpermute_b32 v134, v76, v118
	ds_bpermute_b32 v135, v76, v119
	s_waitcnt lgkmcnt(14)
	v_pk_add_f32 v[104:105], v[104:105], v[120:121]
	s_waitcnt lgkmcnt(12)
	v_pk_add_f32 v[106:107], v[106:107], v[122:123]
	s_waitcnt lgkmcnt(10)
	v_pk_add_f32 v[108:109], v[108:109], v[124:125]
	s_waitcnt lgkmcnt(8)
	v_pk_add_f32 v[110:111], v[110:111], v[126:127]
	s_waitcnt lgkmcnt(6)
	v_pk_add_f32 v[112:113], v[112:113], v[128:129]
	s_waitcnt lgkmcnt(4)
	v_pk_add_f32 v[114:115], v[114:115], v[130:131]
	s_waitcnt lgkmcnt(2)
	v_pk_add_f32 v[116:117], v[116:117], v[132:133]
	s_waitcnt lgkmcnt(0)
	v_pk_add_f32 v[118:119], v[118:119], v[134:135]
	ds_bpermute_b32 v120, v77, v104
	ds_bpermute_b32 v121, v77, v105
	ds_bpermute_b32 v122, v77, v106
	ds_bpermute_b32 v123, v77, v107
	ds_bpermute_b32 v124, v77, v108
	ds_bpermute_b32 v125, v77, v109
	ds_bpermute_b32 v126, v77, v110
	ds_bpermute_b32 v127, v77, v111
	ds_bpermute_b32 v128, v77, v112
	ds_bpermute_b32 v129, v77, v113
	ds_bpermute_b32 v130, v77, v114
	ds_bpermute_b32 v131, v77, v115
	ds_bpermute_b32 v132, v77, v116
	ds_bpermute_b32 v133, v77, v117
	ds_bpermute_b32 v134, v77, v118
	ds_bpermute_b32 v135, v77, v119
	s_waitcnt lgkmcnt(14)
	v_pk_add_f32 v[104:105], v[104:105], v[120:121]
	s_waitcnt lgkmcnt(12)
	v_pk_add_f32 v[106:107], v[106:107], v[122:123]
	s_waitcnt lgkmcnt(10)
	v_pk_add_f32 v[108:109], v[108:109], v[124:125]
	s_waitcnt lgkmcnt(8)
	v_pk_add_f32 v[110:111], v[110:111], v[126:127]
	s_waitcnt lgkmcnt(6)
	v_pk_add_f32 v[112:113], v[112:113], v[128:129]
	s_waitcnt lgkmcnt(4)
	v_pk_add_f32 v[114:115], v[114:115], v[130:131]
	s_waitcnt lgkmcnt(2)
	v_pk_add_f32 v[116:117], v[116:117], v[132:133]
	s_waitcnt lgkmcnt(0)
	v_pk_add_f32 v[118:119], v[118:119], v[134:135]
	ds_bpermute_b32 v120, v78, v104
	ds_bpermute_b32 v121, v78, v105
	ds_bpermute_b32 v122, v78, v106
	ds_bpermute_b32 v123, v78, v107
	ds_bpermute_b32 v124, v78, v108
	ds_bpermute_b32 v125, v78, v109
	ds_bpermute_b32 v126, v78, v110
	ds_bpermute_b32 v127, v78, v111
	ds_bpermute_b32 v128, v78, v112
	ds_bpermute_b32 v129, v78, v113
	ds_bpermute_b32 v130, v78, v114
	ds_bpermute_b32 v131, v78, v115
	ds_bpermute_b32 v132, v78, v116
	ds_bpermute_b32 v133, v78, v117
	ds_bpermute_b32 v134, v78, v118
	ds_bpermute_b32 v135, v78, v119
	s_waitcnt lgkmcnt(14)
	v_pk_add_f32 v[104:105], v[104:105], v[120:121]
	s_waitcnt lgkmcnt(12)
	v_pk_add_f32 v[106:107], v[106:107], v[122:123]
	s_waitcnt lgkmcnt(10)
	v_pk_add_f32 v[108:109], v[108:109], v[124:125]
	s_waitcnt lgkmcnt(8)
	v_pk_add_f32 v[110:111], v[110:111], v[126:127]
	s_waitcnt lgkmcnt(6)
	v_pk_add_f32 v[112:113], v[112:113], v[128:129]
	s_waitcnt lgkmcnt(4)
	v_pk_add_f32 v[114:115], v[114:115], v[130:131]
	s_waitcnt lgkmcnt(2)
	v_pk_add_f32 v[116:117], v[116:117], v[132:133]
	s_waitcnt lgkmcnt(0)
	v_pk_add_f32 v[118:119], v[118:119], v[134:135]
	ds_bpermute_b32 v120, v79, v104
	ds_bpermute_b32 v121, v79, v105
	ds_bpermute_b32 v122, v79, v106
	ds_bpermute_b32 v123, v79, v107
	ds_bpermute_b32 v124, v79, v108
	ds_bpermute_b32 v125, v79, v109
	ds_bpermute_b32 v126, v79, v110
	ds_bpermute_b32 v127, v79, v111
	ds_bpermute_b32 v128, v79, v112
	ds_bpermute_b32 v129, v79, v113
	ds_bpermute_b32 v130, v79, v114
	ds_bpermute_b32 v131, v79, v115
	ds_bpermute_b32 v132, v79, v116
	ds_bpermute_b32 v133, v79, v117
	ds_bpermute_b32 v134, v79, v118
	ds_bpermute_b32 v135, v79, v119
	s_waitcnt lgkmcnt(14)
	v_pk_add_f32 v[104:105], v[104:105], v[120:121]
	s_waitcnt lgkmcnt(12)
	v_pk_add_f32 v[106:107], v[106:107], v[122:123]
	s_waitcnt lgkmcnt(10)
	v_pk_add_f32 v[108:109], v[108:109], v[124:125]
	s_waitcnt lgkmcnt(8)
	v_pk_add_f32 v[110:111], v[110:111], v[126:127]
	s_waitcnt lgkmcnt(6)
	v_pk_add_f32 v[112:113], v[112:113], v[128:129]
	s_waitcnt lgkmcnt(4)
	v_pk_add_f32 v[114:115], v[114:115], v[130:131]
	s_waitcnt lgkmcnt(2)
	v_pk_add_f32 v[116:117], v[116:117], v[132:133]
	s_waitcnt lgkmcnt(0)
	v_pk_add_f32 v[118:119], v[118:119], v[134:135]
	ds_bpermute_b32 v120, v80, v104
	ds_bpermute_b32 v121, v80, v105
	ds_bpermute_b32 v122, v80, v106
	ds_bpermute_b32 v123, v80, v107
	ds_bpermute_b32 v124, v80, v108
	ds_bpermute_b32 v125, v80, v109
	ds_bpermute_b32 v126, v80, v110
	ds_bpermute_b32 v127, v80, v111
	ds_bpermute_b32 v128, v80, v112
	ds_bpermute_b32 v129, v80, v113
	ds_bpermute_b32 v130, v80, v114
	ds_bpermute_b32 v131, v80, v115
	ds_bpermute_b32 v132, v80, v116
	ds_bpermute_b32 v133, v80, v117
	ds_bpermute_b32 v134, v80, v118
	ds_bpermute_b32 v135, v80, v119
	s_waitcnt lgkmcnt(14)
	v_pk_add_f32 v[104:105], v[104:105], v[120:121]
	s_waitcnt lgkmcnt(12)
	v_pk_add_f32 v[106:107], v[106:107], v[122:123]
	s_waitcnt lgkmcnt(10)
	v_pk_add_f32 v[108:109], v[108:109], v[124:125]
	s_waitcnt lgkmcnt(8)
	v_pk_add_f32 v[110:111], v[110:111], v[126:127]
	s_waitcnt lgkmcnt(6)
	v_pk_add_f32 v[112:113], v[112:113], v[128:129]
	s_waitcnt lgkmcnt(4)
	v_pk_add_f32 v[114:115], v[114:115], v[130:131]
	s_waitcnt lgkmcnt(2)
	v_pk_add_f32 v[116:117], v[116:117], v[132:133]
	s_waitcnt lgkmcnt(0)
	v_pk_add_f32 v[118:119], v[118:119], v[134:135]
	s_and_saveexec_b64 s[6:7], vcc
	ds_write2_b32 v81, v104, v105 offset0:0 offset1:1
	ds_write2_b32 v81, v106, v107 offset0:8 offset1:9
	ds_write2_b32 v81, v108, v109 offset0:16 offset1:17
	ds_write2_b32 v81, v110, v111 offset0:24 offset1:25
	ds_write2_b32 v81, v112, v113 offset0:32 offset1:33
	ds_write2_b32 v81, v114, v115 offset0:40 offset1:41
	ds_write2_b32 v81, v116, v117 offset0:48 offset1:49
	ds_write2_b32 v81, v118, v119 offset0:56 offset1:57
	s_or_b64 exec, exec, s[6:7]
